# P6/P10: workgroups that have no sample split-K unit start ~10/13us later so residual epilogues of the two groups do not hit HBM at the same time
# baseline (speedup 1.0000x reference)
.LBB0_930:
	s_cmpk_lt_i32 s44, 0x80
	s_cbranch_scc1 .Lp6_nodelay
	s_sleep 127
	s_sleep 127
	s_sleep 64

.LBB0_1278:
	s_cmpk_lt_i32 s37, 0xb0
	s_cbranch_scc1 .Lp10_nodelay
	s_sleep 127
	s_sleep 127
	s_sleep 127
	s_sleep 127
